# v7 + attention softmax exponentiates scores in place (row-sum order changed), freeing registers so V fragments of the first three column blocks are in flight before P.V starts
# baseline (speedup 1.0000x reference)
; __device__ __forceinline__ void partialSM(f32x16& p0, f32x16& p1, float& m_reg, float& mn, float& alpha) {
;     ...
;   float mnC = -mn * C;
; #pragma unroll
;   for (int r = 0; r < 16; ++r) p0[r] = fmaf(p0[r], C, mnC);
; #pragma unroll
;   for (int r = 0; r < 16; ++r) p1[r] = fmaf(p1[r], C, mnC);
; #pragma unroll
;   for (int r = 0; r < 16; ++r) p0[r] = __builtin_amdgcn_exp2f(p0[r]);
; }
; __device__ __forceinline__ void finishSM(f32x16& p0, f32x16& p1, float alpha, float& l_reg, bf16x8& pa0, bf16x8& pa1, bf16x8& pa2, bf16x8& pa3) {
; #pragma unroll
;   for (int r = 0; r < 16; ++r) p1[r] = __builtin_amdgcn_exp2f(p1[r]);
;   float ps = 0;
; #pragma unroll
;   for (int r = 0; r < 16; ++r) ps += p0[r];
; #pragma unroll
;   for (int r = 0; r < 16; ++r) ps += p1[r];
;   { auto rr = __builtin_amdgcn_permlane32_swap(__float_as_uint(ps), __float_as_uint(ps), false, false);
;     ps = __uint_as_float(rr[0]) + __uint_as_float(rr[1]); }
;   l_reg = l_reg * alpha + ps;
;     ...
;   PK4(p0, 0, pa0); PK4(p0, 8, pa1); PK4(p1, 0, pa2); PK4(p1, 8, pa3);
.LBB0_624:
	v_cndmask_b32_e64 v243, v245, v243, s[8:9]
	v_mul_f32_e32 v245, 0xbe0293ee, v243
	ds_read_b64_tr_b16 v[194:195], v251 offset:512
	ds_read_b64_tr_b16 v[196:197], v251 offset:4608
	ds_read_b64_tr_b16 v[198:199], v251 offset:8704
	ds_read_b64_tr_b16 v[200:201], v251 offset:12800
	ds_read_b64_tr_b16 v[202:203], v251 offset:1024
	ds_read_b64_tr_b16 v[204:205], v251 offset:5120
	ds_read_b64_tr_b16 v[206:207], v251 offset:9216
	ds_read_b64_tr_b16 v[208:209], v251 offset:13312
	v_fmamk_f32 v130, v130, 0x3e0293ee, v245
	v_fmamk_f32 v131, v131, 0x3e0293ee, v245
	v_fmamk_f32 v132, v132, 0x3e0293ee, v245
	v_fmamk_f32 v133, v133, 0x3e0293ee, v245
	v_fmamk_f32 v134, v134, 0x3e0293ee, v245
	v_fmamk_f32 v135, v135, 0x3e0293ee, v245
	v_fmamk_f32 v136, v136, 0x3e0293ee, v245
	v_fmamk_f32 v137, v137, 0x3e0293ee, v245
	v_fmamk_f32 v138, v138, 0x3e0293ee, v245
	v_fmamk_f32 v139, v139, 0x3e0293ee, v245
	v_fmamk_f32 v140, v140, 0x3e0293ee, v245
	v_fmamk_f32 v141, v141, 0x3e0293ee, v245
	v_fmamk_f32 v142, v142, 0x3e0293ee, v245
	v_fmamk_f32 v143, v143, 0x3e0293ee, v245
	v_fmamk_f32 v144, v144, 0x3e0293ee, v245
	v_fmamk_f32 v145, v145, 0x3e0293ee, v245
	v_fmamk_f32 v146, v146, 0x3e0293ee, v245
	v_fmamk_f32 v147, v147, 0x3e0293ee, v245
	v_fmamk_f32 v148, v148, 0x3e0293ee, v245
	v_fmamk_f32 v149, v149, 0x3e0293ee, v245
	v_fmamk_f32 v150, v150, 0x3e0293ee, v245
	v_fmamk_f32 v151, v151, 0x3e0293ee, v245
	v_fmamk_f32 v152, v152, 0x3e0293ee, v245
	v_fmamk_f32 v153, v153, 0x3e0293ee, v245
	v_fmamk_f32 v154, v154, 0x3e0293ee, v245
	v_fmamk_f32 v155, v155, 0x3e0293ee, v245
	v_fmamk_f32 v156, v156, 0x3e0293ee, v245
	v_fmamk_f32 v157, v157, 0x3e0293ee, v245
	v_fmamk_f32 v158, v158, 0x3e0293ee, v245
	v_fmamk_f32 v159, v159, 0x3e0293ee, v245
	v_fmamk_f32 v160, v160, 0x3e0293ee, v245
	v_fmamk_f32 v161, v161, 0x3e0293ee, v245
	v_exp_f32_e32 v130, v130
	v_exp_f32_e32 v131, v131
	v_exp_f32_e32 v132, v132
	v_add_f32_e32 v245, v130, v131
	v_exp_f32_e32 v133, v133
	v_add_f32_e32 v245, v132, v245
	v_exp_f32_e32 v134, v134
	v_add_f32_e32 v245, v133, v245
	v_exp_f32_e32 v135, v135
	v_add_f32_e32 v245, v134, v245
	v_exp_f32_e32 v136, v136
	v_add_f32_e32 v245, v135, v245
	v_exp_f32_e32 v137, v137
	v_add_f32_e32 v245, v136, v245
	v_exp_f32_e32 v138, v138
	v_add_f32_e32 v245, v137, v245
	v_exp_f32_e32 v139, v139
	v_add_f32_e32 v245, v138, v245
	v_exp_f32_e32 v140, v140
	v_add_f32_e32 v245, v139, v245
	v_exp_f32_e32 v141, v141
	v_add_f32_e32 v245, v140, v245
	v_exp_f32_e32 v142, v142
	v_add_f32_e32 v245, v141, v245
	v_exp_f32_e32 v143, v143
	v_add_f32_e32 v245, v142, v245
	v_exp_f32_e32 v144, v144
	v_add_f32_e32 v245, v143, v245
	v_exp_f32_e32 v145, v145
	v_add_f32_e32 v245, v144, v245
	s_nop 0
	v_add_f32_e32 v245, v145, v245
	v_cvt_pk_bf16_f32 v145, v144, v145
	v_cvt_pk_bf16_f32 v144, v142, v143
	v_cvt_pk_bf16_f32 v143, v140, v141
	v_cvt_pk_bf16_f32 v142, v138, v139
	v_cvt_pk_bf16_f32 v141, v136, v137
	v_cvt_pk_bf16_f32 v140, v134, v135
	v_cvt_pk_bf16_f32 v139, v132, v133
	v_cvt_pk_bf16_f32 v138, v130, v131
	v_exp_f32_e32 v146, v146
	v_exp_f32_e32 v147, v147
	v_add_f32_e32 v245, v146, v245
	v_exp_f32_e32 v148, v148
	v_add_f32_e32 v245, v147, v245
	v_exp_f32_e32 v149, v149
	v_add_f32_e32 v245, v148, v245
	v_exp_f32_e32 v150, v150
	v_add_f32_e32 v245, v149, v245
	v_exp_f32_e32 v151, v151
	v_add_f32_e32 v245, v150, v245
	v_exp_f32_e32 v152, v152
	v_add_f32_e32 v245, v151, v245
	v_exp_f32_e32 v153, v153
	v_add_f32_e32 v245, v152, v245
	v_exp_f32_e32 v154, v154
	v_add_f32_e32 v245, v153, v245
	v_exp_f32_e32 v155, v155
	v_add_f32_e32 v245, v154, v245
	v_exp_f32_e32 v156, v156
	v_add_f32_e32 v245, v155, v245
	v_exp_f32_e32 v157, v157
	v_add_f32_e32 v245, v156, v245
	v_exp_f32_e32 v158, v158
	v_add_f32_e32 v245, v157, v245
	v_exp_f32_e32 v159, v159
	v_add_f32_e32 v245, v158, v245
	v_exp_f32_e32 v160, v160
	v_add_f32_e32 v245, v159, v245
	v_exp_f32_e32 v161, v161
	v_add_f32_e32 v245, v160, v245
	s_nop 0
	v_add_f32_e32 v245, v161, v245
	v_cvt_pk_bf16_f32 v130, v146, v147
	v_cvt_pk_bf16_f32 v131, v148, v149
	v_cvt_pk_bf16_f32 v132, v150, v151
	v_cvt_pk_bf16_f32 v133, v152, v153
	v_cvt_pk_bf16_f32 v134, v154, v155
	v_cvt_pk_bf16_f32 v135, v156, v157
	v_cvt_pk_bf16_f32 v136, v158, v159
	v_cvt_pk_bf16_f32 v137, v160, v161
	v_mov_b32_e32 v147, v245
	s_nop 1
	v_permlane32_swap_b32_e32 v245, v147
	v_add_f32_e32 v147, v245, v147
	v_fmac_f32_e32 v147, v244, v1
	v_permlane32_swap_b32_e32 v130, v132
	v_permlane32_swap_b32_e32 v131, v133
	v_permlane32_swap_b32_e32 v134, v136
	v_permlane32_swap_b32_e32 v135, v137
	v_permlane32_swap_b32_e32 v138, v140
	v_permlane32_swap_b32_e32 v139, v141
	v_permlane32_swap_b32_e32 v142, v144
	v_permlane32_swap_b32_e32 v143, v145
	s_nop 1
	s_waitcnt lgkmcnt(8)
	v_mfma_f32_32x32x16_bf16 v[114:129], v[130:133], v[246:249], v[114:129]
	ds_read_b64_tr_b16 v[148:149], v251 offset:1536
	ds_read_b64_tr_b16 v[150:151], v251 offset:5632
	ds_read_b64_tr_b16 v[152:153], v251 offset:9728
	ds_read_b64_tr_b16 v[154:155], v251 offset:13824
	v_mfma_f32_32x32x16_bf16 v[114:129], v[134:137], v[252:255], v[114:129]
	s_waitcnt lgkmcnt(8)
; #define SBAR() __builtin_amdgcn_sched_barrier(0)
; #define STEP(D, CUR, NXT) v_load<D + 1>(NXT, vb); asm volatile("s_waitcnt lgkmcnt(8)" ::: "memory"); SBAR(); pv_mma(o[D], CUR, pa0, pa1, pa2, pa3); SBAR();
; __device__ __forceinline__ void pv_mma(f32x16& od, const VFrag& f, bf16x8 pa0, bf16x8 pa1, bf16x8 pa2, bf16x8 pa3) {
;     ...
;   od = __builtin_amdgcn_mfma_f32_32x32x16_bf16(pa0, PK(f.l0, f.h0), od, 0, 0, 0);
;   od = __builtin_amdgcn_mfma_f32_32x32x16_bf16(pa1, PK(f.l1, f.h1), od, 0, 0, 0);
;   od = __builtin_amdgcn_mfma_f32_32x32x16_bf16(pa2, PK(f.l2, f.h2), od, 0, 0, 0);
;   od = __builtin_amdgcn_mfma_f32_32x32x16_bf16(pa3, PK(f.l3, f.h3), od, 0, 0, 0);
;     ...
; }
; __device__ __forceinline__ void pv_all(f32x16* o, int vb, bf16x8 pa0, bf16x8 pa1, bf16x8 pa2, bf16x8 pa3) {
;   VFrag fa, fb;
;   v_load<0>(fa, vb);
;     ...
;   STEP(0, fa, fb) STEP(1, fb, fa) STEP(2, fa, fb) STEP(3, fb, fa) STEP(4, fa, fb) STEP(5, fb, fa) STEP(6, fa, fb)
;     ...
;   asm volatile("s_waitcnt lgkmcnt(0)" ::: "memory"); SBAR(); pv_mma(o[7], fb, pa0, pa1, pa2, pa3);
; }
; __device__ __forceinline__ void body(const bf16_t* __restrict__ Qb, const bf16_t* __restrict__ Kh, const bf16_t* __restrict__ Vh, bf16_t* __restrict__ Ob, int seq, char* lds) {
;     ...
;     asm volatile("s_waitcnt vmcnt(0) lgkmcnt(0)" ::: "memory"); __builtin_amdgcn_s_barrier(); asm volatile("" ::: "memory");
;   }
;   __builtin_amdgcn_s_setprio(0);
;   if (hi == 0) li_l[r32] = l_reg; asm volatile("s_waitcnt lgkmcnt(0)" ::: "memory");
	v_mfma_f32_32x32x16_bf16 v[98:113], v[130:133], v[194:197], v[98:113]
	ds_read_b64_tr_b16 v[156:157], v251 offset:2048
	ds_read_b64_tr_b16 v[158:159], v251 offset:6144
	ds_read_b64_tr_b16 v[244:245], v251 offset:10240
	ds_read_b64_tr_b16 v[246:247], v251 offset:14336
	v_mfma_f32_32x32x16_bf16 v[98:113], v[134:137], v[198:201], v[98:113]
	s_waitcnt lgkmcnt(8)
	v_mfma_f32_32x32x16_bf16 v[82:97], v[130:133], v[202:205], v[82:97]
	ds_read_b64_tr_b16 v[194:195], v251 offset:2560
	ds_read_b64_tr_b16 v[196:197], v251 offset:6656
	ds_read_b64_tr_b16 v[198:199], v251 offset:10752
	ds_read_b64_tr_b16 v[200:201], v251 offset:14848
	v_mfma_f32_32x32x16_bf16 v[82:97], v[134:137], v[206:209], v[82:97]
	s_waitcnt lgkmcnt(8)
	v_mfma_f32_32x32x16_bf16 v[66:81], v[130:133], v[148:151], v[66:81]
	ds_read_b64_tr_b16 v[202:203], v251 offset:3072
	ds_read_b64_tr_b16 v[204:205], v251 offset:7168
	ds_read_b64_tr_b16 v[206:207], v251 offset:11264
	ds_read_b64_tr_b16 v[208:209], v251 offset:15360
	v_mfma_f32_32x32x16_bf16 v[66:81], v[134:137], v[152:155], v[66:81]
	s_waitcnt lgkmcnt(8)
	v_mfma_f32_32x32x16_bf16 v[50:65], v[130:133], v[156:159], v[50:65]
	ds_read_b64_tr_b16 v[148:149], v251 offset:3584
	ds_read_b64_tr_b16 v[150:151], v251 offset:7680
	ds_read_b64_tr_b16 v[152:153], v251 offset:11776
	ds_read_b64_tr_b16 v[154:155], v251 offset:15872
	v_mfma_f32_32x32x16_bf16 v[50:65], v[134:137], v[244:247], v[50:65]
	s_waitcnt lgkmcnt(8)
	v_mfma_f32_32x32x16_bf16 v[34:49], v[130:133], v[194:197], v[34:49]
	ds_read_b64_tr_b16 v[156:157], v251 offset:16384
	ds_read_b64_tr_b16 v[158:159], v251 offset:20480
	ds_read_b64_tr_b16 v[244:245], v251 offset:24576
	ds_read_b64_tr_b16 v[246:247], v251 offset:28672
	v_mfma_f32_32x32x16_bf16 v[34:49], v[134:137], v[198:201], v[34:49]
	s_waitcnt lgkmcnt(8)
	v_mfma_f32_32x32x16_bf16 v[18:33], v[130:133], v[202:205], v[18:33]
	ds_read_b64_tr_b16 v[194:195], v251 offset:16896
	ds_read_b64_tr_b16 v[196:197], v251 offset:20992
	ds_read_b64_tr_b16 v[198:199], v251 offset:25088
	ds_read_b64_tr_b16 v[200:201], v251 offset:29184
	v_mfma_f32_32x32x16_bf16 v[18:33], v[134:137], v[206:209], v[18:33]
	s_waitcnt lgkmcnt(8)
	v_mfma_f32_32x32x16_bf16 v[2:17], v[130:133], v[148:151], v[2:17]
	ds_read_b64_tr_b16 v[202:203], v251 offset:17408
	ds_read_b64_tr_b16 v[204:205], v251 offset:21504
	ds_read_b64_tr_b16 v[206:207], v251 offset:25600
	ds_read_b64_tr_b16 v[208:209], v251 offset:29696
	v_mfma_f32_32x32x16_bf16 v[2:17], v[134:137], v[152:155], v[2:17]
	s_waitcnt lgkmcnt(8)
	v_mfma_f32_32x32x16_bf16 v[114:129], v[138:141], v[156:159], v[114:129]
	ds_read_b64_tr_b16 v[148:149], v251 offset:17920
	ds_read_b64_tr_b16 v[150:151], v251 offset:22016
	ds_read_b64_tr_b16 v[152:153], v251 offset:26112
	ds_read_b64_tr_b16 v[154:155], v251 offset:30208
	v_mfma_f32_32x32x16_bf16 v[114:129], v[142:145], v[244:247], v[114:129]
	s_waitcnt lgkmcnt(8)
	v_mfma_f32_32x32x16_bf16 v[98:113], v[138:141], v[194:197], v[98:113]
	ds_read_b64_tr_b16 v[156:157], v251 offset:18432
	ds_read_b64_tr_b16 v[158:159], v251 offset:22528
	ds_read_b64_tr_b16 v[244:245], v251 offset:26624
	ds_read_b64_tr_b16 v[246:247], v251 offset:30720
	v_mfma_f32_32x32x16_bf16 v[98:113], v[142:145], v[198:201], v[98:113]
	s_waitcnt lgkmcnt(8)
	v_mfma_f32_32x32x16_bf16 v[82:97], v[138:141], v[202:205], v[82:97]
	ds_read_b64_tr_b16 v[194:195], v251 offset:18944
	ds_read_b64_tr_b16 v[196:197], v251 offset:23040
	ds_read_b64_tr_b16 v[198:199], v251 offset:27136
	ds_read_b64_tr_b16 v[200:201], v251 offset:31232
	v_mfma_f32_32x32x16_bf16 v[82:97], v[142:145], v[206:209], v[82:97]
	s_waitcnt lgkmcnt(8)
	v_mfma_f32_32x32x16_bf16 v[66:81], v[138:141], v[148:151], v[66:81]
	ds_read_b64_tr_b16 v[202:203], v251 offset:19456
	ds_read_b64_tr_b16 v[204:205], v251 offset:23552
	ds_read_b64_tr_b16 v[206:207], v251 offset:27648
	ds_read_b64_tr_b16 v[208:209], v251 offset:31744
	v_mfma_f32_32x32x16_bf16 v[66:81], v[142:145], v[152:155], v[66:81]
	s_waitcnt lgkmcnt(8)
	v_mfma_f32_32x32x16_bf16 v[50:65], v[138:141], v[156:159], v[50:65]
	ds_read_b64_tr_b16 v[148:149], v251 offset:19968
	ds_read_b64_tr_b16 v[150:151], v251 offset:24064
	ds_read_b64_tr_b16 v[152:153], v251 offset:28160
	ds_read_b64_tr_b16 v[154:155], v251 offset:32256
	v_mfma_f32_32x32x16_bf16 v[50:65], v[142:145], v[244:247], v[50:65]
	s_waitcnt lgkmcnt(8)
	v_mfma_f32_32x32x16_bf16 v[34:49], v[138:141], v[194:197], v[34:49]
	v_mfma_f32_32x32x16_bf16 v[34:49], v[142:145], v[198:201], v[34:49]
	s_waitcnt lgkmcnt(4)
	v_mfma_f32_32x32x16_bf16 v[18:33], v[138:141], v[202:205], v[18:33]
	v_mfma_f32_32x32x16_bf16 v[18:33], v[142:145], v[206:209], v[18:33]
	s_waitcnt vmcnt(0) lgkmcnt(0)
	s_barrier
	s_and_b32 s8, s29, 1
	s_lshl_b32 s8, s8, 14
	s_add_i32 s8, s8, 0x10010
	v_add3_u32 v1, s8, v233, v213
	ds_read_b128 v[194:197], v1
	ds_read_b128 v[198:201], v1 offset:8192
	v_add3_u32 v1, s8, v234, v213
	ds_read_b128 v[202:205], v1
	ds_read_b128 v[206:209], v1 offset:8192
	v_add3_u32 v1, s8, v235, v213
	ds_read_b128 v[246:249], v1
	ds_read_b128 v[252:255], v1 offset:8192
	s_cmp_eq_u32 s24, s29
	v_mfma_f32_32x32x16_bf16 v[2:17], v[138:141], v[148:151], v[2:17]
	v_mfma_f32_32x32x16_bf16 v[2:17], v[142:145], v[152:155], v[2:17]
	s_cbranch_scc1 .LBB0_626
	v_mov_b32_e32 v244, v147
	s_branch .LBB0_616
.LBB0_626:
	s_setprio 0
	s_and_saveexec_b64 s[8:9], s[6:7]
	s_cbranch_execz .LBB0_607
	ds_write_b32 v237, v147
	s_branch .LBB0_607
